# attention loop edge: dead remainder-loop bookkeeping removed from the back edge
# baseline (speedup 1.0000x reference)
.Lattn_noprio:
	s_mov_b32 s100, -1
	s_mov_b32 s99, 0
	ds_read_b128 v[222:225], v186 offset:9216
	ds_read_b128 v[226:229], v186 offset:13824
	ds_read_b128 v[230:233], v186 offset:9248
	ds_read_b128 v[234:237], v186 offset:13856
	ds_read_b128 v[138:141], v186 offset:9280
	ds_read_b128 v[142:145], v186 offset:13888
	ds_read_b128 v[162:165], v186 offset:9312
	ds_read_b128 v[132:135], v186 offset:13920
	v_exp_f32_e32 v32, v32
	v_exp_f32_e32 v33, v33
	v_exp_f32_e32 v34, v34
	v_exp_f32_e32 v35, v35
	v_exp_f32_e32 v36, v36
	v_exp_f32_e32 v37, v37
	v_exp_f32_e32 v38, v38
	v_exp_f32_e32 v39, v39
	v_exp_f32_e32 v40, v40
	v_exp_f32_e32 v41, v41
	v_exp_f32_e32 v42, v42
	v_exp_f32_e32 v43, v43
	v_exp_f32_e32 v44, v44
	v_exp_f32_e32 v45, v45
	v_exp_f32_e32 v46, v46
	v_exp_f32_e32 v47, v47
.Lattn_main:
	s_waitcnt lgkmcnt(7)
	v_mfma_f32_32x32x16_bf16 v[64:79], v[222:225], v[96:99], 0
	ds_read_b128 v[222:225], v186 offset:36864
	v_add_f32_e32 v188, v188, v32
	v_add_f32_e32 v189, v189, v33
	v_cvt_pk_bf16_f32 v32, v32, v33
	v_add_f32_e32 v190, v190, v34
	v_add_f32_e32 v191, v191, v35
	v_cvt_pk_bf16_f32 v33, v34, v35
	v_exp_f32_e32 v48, v48
	v_exp_f32_e32 v49, v49
	s_waitcnt lgkmcnt(7)
	v_mfma_f32_32x32x16_bf16 v[206:221], v[226:229], v[96:99], 0
	ds_read_b128 v[226:229], v186 offset:41472
	v_add_f32_e32 v192, v192, v36
	v_add_f32_e32 v193, v193, v37
	v_cvt_pk_bf16_f32 v34, v36, v37
	v_exp_f32_e32 v50, v50
	v_exp_f32_e32 v51, v51
	s_waitcnt lgkmcnt(7)
	v_mfma_f32_32x32x16_bf16 v[64:79], v[230:233], v[100:103], v[64:79]
	ds_read_b128 v[230:233], v186 offset:36896
	v_add_f32_e32 v194, v194, v38
	v_add_f32_e32 v195, v195, v39
	v_cvt_pk_bf16_f32 v35, v38, v39
	v_exp_f32_e32 v52, v52
	v_exp_f32_e32 v53, v53
	s_waitcnt lgkmcnt(7)
	v_mfma_f32_32x32x16_bf16 v[206:221], v[234:237], v[100:103], v[206:221]
	ds_read_b128 v[234:237], v186 offset:41504
	v_add_f32_e32 v196, v196, v40
	v_add_f32_e32 v197, v197, v41
	v_cvt_pk_bf16_f32 v36, v40, v41
	v_exp_f32_e32 v54, v54
	v_exp_f32_e32 v55, v55
	s_waitcnt lgkmcnt(7)
	v_mfma_f32_32x32x16_bf16 v[64:79], v[138:141], v[104:107], v[64:79]
	ds_read_b128 v[138:141], v186 offset:36928
	v_add_f32_e32 v198, v198, v42
	v_add_f32_e32 v199, v199, v43
	v_cvt_pk_bf16_f32 v37, v42, v43
	v_exp_f32_e32 v56, v56
	v_exp_f32_e32 v57, v57
	s_waitcnt lgkmcnt(7)
	v_mfma_f32_32x32x16_bf16 v[206:221], v[142:145], v[104:107], v[206:221]
	ds_read_b128 v[142:145], v186 offset:41536
	v_add_f32_e32 v200, v200, v44
	v_add_f32_e32 v201, v201, v45
	v_cvt_pk_bf16_f32 v38, v44, v45
	v_exp_f32_e32 v58, v58
	v_exp_f32_e32 v59, v59
	s_waitcnt lgkmcnt(7)
	v_mfma_f32_32x32x16_bf16 v[64:79], v[162:165], v[108:111], v[64:79]
	ds_read_b128 v[162:165], v186 offset:36960
	v_add_f32_e32 v202, v202, v46
	v_add_f32_e32 v203, v203, v47
	v_cvt_pk_bf16_f32 v39, v46, v47
	v_exp_f32_e32 v60, v60
	v_exp_f32_e32 v61, v61
	s_waitcnt lgkmcnt(7)
	v_mfma_f32_32x32x16_bf16 v[206:221], v[132:135], v[108:111], v[206:221]
	ds_read_b128 v[132:135], v186 offset:41568
	v_add_f32_e32 v188, v188, v48
	v_add_f32_e32 v189, v189, v49
	v_cvt_pk_bf16_f32 v48, v48, v49
	v_add_f32_e32 v190, v190, v50
	v_add_f32_e32 v191, v191, v51
	v_cvt_pk_bf16_f32 v49, v50, v51
	v_exp_f32_e32 v62, v62
	v_exp_f32_e32 v63, v63
	s_waitcnt lgkmcnt(7)
	v_mfma_f32_32x32x16_bf16 v[0:15], v[222:225], v[32:35], v[0:15]
	ds_read_b128 v[222:225], v186 offset:18432
	v_add_f32_e32 v192, v192, v52
	v_add_f32_e32 v193, v193, v53
	v_cvt_pk_bf16_f32 v50, v52, v53
	v_exp_f32_e32 v64, v64
	v_exp_f32_e32 v65, v65
	s_waitcnt lgkmcnt(7)
	v_mfma_f32_32x32x16_bf16 v[16:31], v[226:229], v[32:35], v[16:31]
	ds_read_b128 v[226:229], v186 offset:23040
	v_add_f32_e32 v194, v194, v54
	v_add_f32_e32 v195, v195, v55
	v_cvt_pk_bf16_f32 v51, v54, v55
	v_exp_f32_e32 v66, v66
	v_exp_f32_e32 v67, v67
	s_waitcnt lgkmcnt(7)
	v_mfma_f32_32x32x16_bf16 v[0:15], v[230:233], v[36:39], v[0:15]
	ds_read_b128 v[230:233], v186 offset:18464
	v_add_f32_e32 v196, v196, v56
	v_add_f32_e32 v197, v197, v57
	v_cvt_pk_bf16_f32 v52, v56, v57
	v_exp_f32_e32 v68, v68
	v_exp_f32_e32 v69, v69
	v_add_u32_e32 v204, 0xd800, v136
	v_add_u32_e32 v205, 0xf800, v136
	s_waitcnt vmcnt(3)
	ds_write_b128 v168, v[112:115] offset:27648
	s_waitcnt vmcnt(2)
	s_waitcnt lgkmcnt(8)
	v_mfma_f32_32x32x16_bf16 v[16:31], v[234:237], v[36:39], v[16:31]
	ds_read_b128 v[234:237], v186 offset:23072
	v_add_f32_e32 v198, v198, v58
	v_add_f32_e32 v199, v199, v59
	v_cvt_pk_bf16_f32 v53, v58, v59
	v_exp_f32_e32 v70, v70
	v_exp_f32_e32 v71, v71
	ds_write_b128 v168, v[116:119]
	s_waitcnt vmcnt(1)
	ds_write2_b64 v204, v[120:121], v[122:123] offset1:2
	s_waitcnt vmcnt(0)
	ds_write2_b64 v205, v[124:125], v[126:127] offset0:128 offset1:130
	s_waitcnt lgkmcnt(11)
	v_mfma_f32_32x32x16_bf16 v[0:15], v[138:141], v[48:51], v[0:15]
	ds_read_b128 v[138:141], v186 offset:18496
	v_add_f32_e32 v200, v200, v60
	v_add_f32_e32 v201, v201, v61
	v_cvt_pk_bf16_f32 v54, v60, v61
	v_exp_f32_e32 v72, v72
	v_exp_f32_e32 v73, v73
	v_lshl_add_u64 v[120:121], v[128:129], 0, v[150:151]
	v_lshl_add_u64 v[124:125], v[130:131], 0, v[150:151]
	s_mov_b32 s98, 0xd8c8000
	v_lshl_add_u64 v[146:147], v[120:121], 0, s[98:99]
	global_load_dwordx4 v[80:83], v[146:147], off offset:2304
	s_waitcnt lgkmcnt(11)
	v_mfma_f32_32x32x16_bf16 v[16:31], v[142:145], v[48:51], v[16:31]
	ds_read_b128 v[142:145], v186 offset:23104
	v_add_f32_e32 v202, v202, v62
	v_add_f32_e32 v203, v203, v63
	v_cvt_pk_bf16_f32 v55, v62, v63
	v_exp_f32_e32 v74, v74
	v_exp_f32_e32 v75, v75
	s_mov_b32 s98, 0xd8f0000
	v_lshl_add_u64 v[146:147], v[120:121], 0, s[98:99]
	global_load_dwordx4 v[84:87], v[146:147], off offset:2304
	s_mov_b32 s98, 0x17820000
	v_lshl_add_u64 v[146:147], v[124:125], 0, s[98:99]
	s_waitcnt lgkmcnt(11)
; __device__ __forceinline__ void attn_global(LAS unsigned char* lds, const bf16_t* __restrict__ PROJ, const bf16_t* __restrict__ VT, bf16_t* __restrict__ AO,
;                                             int rowbase, int S, int hq, int q0, float bound2) {
;     ...
;     int t = 0;
; #pragma unroll 1
;     for (; t + 10 < T; t += 4) { ATT_DSTEP(t, 0, true); ATT_DSTEP(t + 2, 2, true); }
	v_mfma_f32_32x32x16_bf16 v[0:15], v[162:165], v[52:55], v[0:15]
	ds_read_b128 v[162:165], v186 offset:18528
	v_exp_f32_e32 v76, v76
	v_exp_f32_e32 v77, v77
	global_load_dwordx4 v[88:91], v[146:147], off
	s_mov_b32 s98, 0x17828000
	v_lshl_add_u64 v[146:147], v[124:125], 0, s[98:99]
	global_load_dwordx4 v[92:95], v[146:147], off
	v_lshl_add_u64 v[128:129], v[128:129], 0, s[26:27]
	s_waitcnt lgkmcnt(11)
	v_mfma_f32_32x32x16_bf16 v[16:31], v[132:135], v[52:55], v[16:31]
	ds_read_b128 v[132:135], v186 offset:23136
	v_exp_f32_e32 v78, v78
	v_exp_f32_e32 v79, v79
	v_lshl_add_u64 v[130:131], v[130:131], 0, s[28:29]
	s_add_i32 s6, s6, 4
	s_waitcnt lgkmcnt(11)
	v_mfma_f32_32x32x16_bf16 v[32:47], v[222:225], v[96:99], 0
	ds_read_b128 v[222:225], v186 offset:46080
	v_add_f32_e32 v188, v188, v64
	v_add_f32_e32 v189, v189, v65
	v_cvt_pk_bf16_f32 v64, v64, v65
	v_add_f32_e32 v190, v190, v66
	v_add_f32_e32 v191, v191, v67
	v_cvt_pk_bf16_f32 v65, v66, v67
	v_exp_f32_e32 v206, v206
	v_exp_f32_e32 v207, v207
	s_waitcnt lgkmcnt(11)
	v_mfma_f32_32x32x16_bf16 v[48:63], v[226:229], v[96:99], 0
	ds_read_b128 v[226:229], v186 offset:50688
	v_add_f32_e32 v192, v192, v68
	v_add_f32_e32 v193, v193, v69
	v_cvt_pk_bf16_f32 v66, v68, v69
	v_exp_f32_e32 v208, v208
	v_exp_f32_e32 v209, v209
	s_waitcnt lgkmcnt(11)
	v_mfma_f32_32x32x16_bf16 v[32:47], v[230:233], v[100:103], v[32:47]
	ds_read_b128 v[230:233], v186 offset:46112
	v_add_f32_e32 v194, v194, v70
	v_add_f32_e32 v195, v195, v71
	v_cvt_pk_bf16_f32 v67, v70, v71
	v_exp_f32_e32 v210, v210
	v_exp_f32_e32 v211, v211
	s_waitcnt lgkmcnt(10)
	v_mfma_f32_32x32x16_bf16 v[48:63], v[234:237], v[100:103], v[48:63]
	ds_read_b128 v[234:237], v186 offset:50720
	v_add_f32_e32 v196, v196, v72
	v_add_f32_e32 v197, v197, v73
	v_cvt_pk_bf16_f32 v68, v72, v73
	v_exp_f32_e32 v212, v212
	v_exp_f32_e32 v213, v213
	s_waitcnt lgkmcnt(7)
	v_mfma_f32_32x32x16_bf16 v[32:47], v[138:141], v[104:107], v[32:47]
	ds_read_b128 v[138:141], v186 offset:46144
	v_add_f32_e32 v198, v198, v74
	v_add_f32_e32 v199, v199, v75
	v_cvt_pk_bf16_f32 v69, v74, v75
	v_exp_f32_e32 v214, v214
	v_exp_f32_e32 v215, v215
	s_waitcnt lgkmcnt(7)
	v_mfma_f32_32x32x16_bf16 v[48:63], v[142:145], v[104:107], v[48:63]
	ds_read_b128 v[142:145], v186 offset:50752
	v_add_f32_e32 v200, v200, v76
	v_add_f32_e32 v201, v201, v77
	v_cvt_pk_bf16_f32 v70, v76, v77
	v_exp_f32_e32 v216, v216
	v_exp_f32_e32 v217, v217
	s_waitcnt lgkmcnt(7)
	v_mfma_f32_32x32x16_bf16 v[32:47], v[162:165], v[108:111], v[32:47]
	ds_read_b128 v[162:165], v186 offset:46176
	v_add_f32_e32 v202, v202, v78
	v_add_f32_e32 v203, v203, v79
	v_cvt_pk_bf16_f32 v71, v78, v79
	v_exp_f32_e32 v218, v218
	v_exp_f32_e32 v219, v219
	s_waitcnt lgkmcnt(7)
	v_mfma_f32_32x32x16_bf16 v[48:63], v[132:135], v[108:111], v[48:63]
	ds_read_b128 v[132:135], v186 offset:50784
	v_add_f32_e32 v188, v188, v206
	v_add_f32_e32 v189, v189, v207
	v_cvt_pk_bf16_f32 v206, v206, v207
	v_add_f32_e32 v190, v190, v208
	v_add_f32_e32 v191, v191, v209
	v_cvt_pk_bf16_f32 v207, v208, v209
	v_exp_f32_e32 v220, v220
	v_exp_f32_e32 v221, v221
	s_waitcnt lgkmcnt(7)
	v_mfma_f32_32x32x16_bf16 v[0:15], v[222:225], v[64:67], v[0:15]
	v_add_f32_e32 v192, v192, v210
	v_add_f32_e32 v193, v193, v211
	v_cvt_pk_bf16_f32 v208, v210, v211
	v_exp_f32_e32 v32, v32
	v_exp_f32_e32 v33, v33
	s_waitcnt lgkmcnt(6)
	v_mfma_f32_32x32x16_bf16 v[16:31], v[226:229], v[64:67], v[16:31]
	v_add_f32_e32 v194, v194, v212
	v_add_f32_e32 v195, v195, v213
	v_cvt_pk_bf16_f32 v209, v212, v213
	v_exp_f32_e32 v34, v34
	v_exp_f32_e32 v35, v35
	s_waitcnt lgkmcnt(5)
	v_mfma_f32_32x32x16_bf16 v[0:15], v[230:233], v[68:71], v[0:15]
	v_add_f32_e32 v196, v196, v214
	v_add_f32_e32 v197, v197, v215
	v_cvt_pk_bf16_f32 v210, v214, v215
	v_exp_f32_e32 v36, v36
	v_exp_f32_e32 v37, v37
	s_waitcnt lgkmcnt(4)
	v_mfma_f32_32x32x16_bf16 v[16:31], v[234:237], v[68:71], v[16:31]
	s_waitcnt lgkmcnt(0)
	s_barrier
	ds_read_b128 v[222:225], v186 offset:27648
	ds_read_b128 v[226:229], v186 offset:32256
	ds_read_b128 v[230:233], v186 offset:27680
	ds_read_b128 v[234:237], v186 offset:32288
	v_add_f32_e32 v198, v198, v216
	v_add_f32_e32 v199, v199, v217
	v_cvt_pk_bf16_f32 v211, v216, v217
	v_exp_f32_e32 v38, v38
	v_exp_f32_e32 v39, v39
	v_mfma_f32_32x32x16_bf16 v[0:15], v[138:141], v[206:209], v[0:15]
	ds_read_b128 v[138:141], v186 offset:27712
	v_add_f32_e32 v200, v200, v218
	v_add_f32_e32 v201, v201, v219
	v_cvt_pk_bf16_f32 v212, v218, v219
	v_exp_f32_e32 v40, v40
	v_exp_f32_e32 v41, v41
	v_mfma_f32_32x32x16_bf16 v[16:31], v[142:145], v[206:209], v[16:31]
	ds_read_b128 v[142:145], v186 offset:32320
	v_add_f32_e32 v202, v202, v220
	v_add_f32_e32 v203, v203, v221
	v_cvt_pk_bf16_f32 v213, v220, v221
	v_exp_f32_e32 v42, v42
	v_exp_f32_e32 v43, v43
	v_mfma_f32_32x32x16_bf16 v[0:15], v[162:165], v[210:213], v[0:15]
	ds_read_b128 v[162:165], v186 offset:27744
	v_exp_f32_e32 v44, v44
	v_exp_f32_e32 v45, v45
	v_mfma_f32_32x32x16_bf16 v[16:31], v[132:135], v[210:213], v[16:31]
	ds_read_b128 v[132:135], v186 offset:32352
	v_exp_f32_e32 v46, v46
	v_exp_f32_e32 v47, v47
	s_waitcnt lgkmcnt(7)
	v_mfma_f32_32x32x16_bf16 v[64:79], v[222:225], v[96:99], 0
	ds_read_b128 v[222:225], v186 offset:55296
	v_add_f32_e32 v188, v188, v32
	v_add_f32_e32 v189, v189, v33
	v_cvt_pk_bf16_f32 v32, v32, v33
	v_add_f32_e32 v190, v190, v34
	v_add_f32_e32 v191, v191, v35
	v_cvt_pk_bf16_f32 v33, v34, v35
	v_exp_f32_e32 v48, v48
	v_exp_f32_e32 v49, v49
	s_waitcnt lgkmcnt(7)
	v_mfma_f32_32x32x16_bf16 v[206:221], v[226:229], v[96:99], 0
	ds_read_b128 v[226:229], v186 offset:59904
	v_add_f32_e32 v192, v192, v36
	v_add_f32_e32 v193, v193, v37
	v_cvt_pk_bf16_f32 v34, v36, v37
	v_exp_f32_e32 v50, v50
	v_exp_f32_e32 v51, v51
	s_waitcnt lgkmcnt(7)
; #define LAS __attribute__((address_space(3)))
; #define ATT_BAR() asm volatile("s_waitcnt lgkmcnt(0)\n\ts_barrier" ::: "memory")
; #define STV(slot, reg) do { *(LAS u32x2*)(lds + (slot) * TB + vdst) = (u32x2){(reg).x, (reg).y}; *(LAS u32x2*)(lds + (slot) * TB + vdst + 16) = (u32x2){(reg).z, (reg).w}; } while (0)
; __device__ __forceinline__ void attn_global(LAS unsigned char* lds, const bf16_t* __restrict__ PROJ, const bf16_t* __restrict__ VT, bf16_t* __restrict__ AO,
;                                             int rowbase, int S, int hq, int q0, float bound2) {
;     ...
;     u32x4 kra, krb, vra, vrb;
;     kra = LDK(0); krb = LDK(1); vra = LDV(0); vrb = LDV(1);
;     STK(0, kra); STK(1, krb); STV(0, vra); STV(1, vrb);
;     kra = LDK(2); STK(2, kra);
;     kra = LDK(3); krb = LDK(4); vra = LDV(2); vrb = LDV(3);
;     const f32x16 zero16 = {};
;     float ls[16];
; #pragma unroll
;     for (int i = 0; i < 16; ++i) ls[i] = 0.f;
;     f32x16 o0 = {}, o1 = {}, sA, sB, nA, nB;
;     const LAS unsigned char* kfb = lds + RK + r32 * KP + hi * 16;
;     const LAS unsigned char* vfb = lds + RV + r32 * KP + hi * 16;
;     ...
;     ATT_BAR();
;     QK_TILE(sA, sB, 0);
;     ATT_BAR();
	v_mfma_f32_32x32x16_bf16 v[64:79], v[230:233], v[100:103], v[64:79]
	ds_read_b128 v[230:233], v186 offset:55328
	v_add_f32_e32 v194, v194, v38
	v_add_f32_e32 v195, v195, v39
	v_cvt_pk_bf16_f32 v35, v38, v39
	v_exp_f32_e32 v52, v52
	v_exp_f32_e32 v53, v53
	s_waitcnt lgkmcnt(7)
	v_mfma_f32_32x32x16_bf16 v[206:221], v[234:237], v[100:103], v[206:221]
	ds_read_b128 v[234:237], v186 offset:59936
	v_add_f32_e32 v196, v196, v40
	v_add_f32_e32 v197, v197, v41
	v_cvt_pk_bf16_f32 v36, v40, v41
	v_exp_f32_e32 v54, v54
	v_exp_f32_e32 v55, v55
	s_waitcnt lgkmcnt(7)
	v_mfma_f32_32x32x16_bf16 v[64:79], v[138:141], v[104:107], v[64:79]
	ds_read_b128 v[138:141], v186 offset:55360
	v_add_f32_e32 v198, v198, v42
	v_add_f32_e32 v199, v199, v43
	v_cvt_pk_bf16_f32 v37, v42, v43
	v_exp_f32_e32 v56, v56
	v_exp_f32_e32 v57, v57
	s_waitcnt lgkmcnt(7)
	v_mfma_f32_32x32x16_bf16 v[206:221], v[142:145], v[104:107], v[206:221]
	ds_read_b128 v[142:145], v186 offset:59968
	v_add_f32_e32 v200, v200, v44
	v_add_f32_e32 v201, v201, v45
	v_cvt_pk_bf16_f32 v38, v44, v45
	v_exp_f32_e32 v58, v58
	v_exp_f32_e32 v59, v59
	s_waitcnt lgkmcnt(7)
	v_mfma_f32_32x32x16_bf16 v[64:79], v[162:165], v[108:111], v[64:79]
	ds_read_b128 v[162:165], v186 offset:55392
	v_add_f32_e32 v202, v202, v46
	v_add_f32_e32 v203, v203, v47
	v_cvt_pk_bf16_f32 v39, v46, v47
	v_exp_f32_e32 v60, v60
	v_exp_f32_e32 v61, v61
	s_waitcnt lgkmcnt(7)
	v_mfma_f32_32x32x16_bf16 v[206:221], v[132:135], v[108:111], v[206:221]
	ds_read_b128 v[132:135], v186 offset:60000
	v_add_f32_e32 v188, v188, v48
	v_add_f32_e32 v189, v189, v49
	v_cvt_pk_bf16_f32 v48, v48, v49
	v_add_f32_e32 v190, v190, v50
	v_add_f32_e32 v191, v191, v51
	v_cvt_pk_bf16_f32 v49, v50, v51
	v_exp_f32_e32 v62, v62
	v_exp_f32_e32 v63, v63
	s_waitcnt lgkmcnt(7)
	v_mfma_f32_32x32x16_bf16 v[0:15], v[222:225], v[32:35], v[0:15]
	ds_read_b128 v[222:225], v186
	v_add_f32_e32 v192, v192, v52
	v_add_f32_e32 v193, v193, v53
	v_cvt_pk_bf16_f32 v50, v52, v53
	v_exp_f32_e32 v64, v64
	v_exp_f32_e32 v65, v65
	s_waitcnt lgkmcnt(7)
	v_mfma_f32_32x32x16_bf16 v[16:31], v[226:229], v[32:35], v[16:31]
	ds_read_b128 v[226:229], v186 offset:4608
	v_add_f32_e32 v194, v194, v54
	v_add_f32_e32 v195, v195, v55
	v_cvt_pk_bf16_f32 v51, v54, v55
	v_exp_f32_e32 v66, v66
	v_exp_f32_e32 v67, v67
	s_waitcnt lgkmcnt(7)
	v_mfma_f32_32x32x16_bf16 v[0:15], v[230:233], v[36:39], v[0:15]
	ds_read_b128 v[230:233], v186 offset:32
	v_add_f32_e32 v196, v196, v56
	v_add_f32_e32 v197, v197, v57
	v_cvt_pk_bf16_f32 v52, v56, v57
	v_exp_f32_e32 v68, v68
	v_exp_f32_e32 v69, v69
	s_waitcnt vmcnt(3)
	ds_write_b128 v168, v[80:83] offset:9216
	s_waitcnt vmcnt(2)
	ds_write_b128 v168, v[84:87] offset:18432
	s_waitcnt lgkmcnt(9)
	v_mfma_f32_32x32x16_bf16 v[16:31], v[234:237], v[36:39], v[16:31]
	ds_read_b128 v[234:237], v186 offset:4640
	v_add_f32_e32 v198, v198, v58
	v_add_f32_e32 v199, v199, v59
	v_cvt_pk_bf16_f32 v53, v58, v59
	v_exp_f32_e32 v70, v70
	v_exp_f32_e32 v71, v71
	s_waitcnt vmcnt(1)
	ds_write2_b64 v169, v[88:89], v[90:91] offset1:2
	s_waitcnt vmcnt(0)
	ds_write2_b64 v170, v[92:93], v[94:95] offset0:128 offset1:130
	s_waitcnt lgkmcnt(11)
	v_mfma_f32_32x32x16_bf16 v[0:15], v[138:141], v[48:51], v[0:15]
	ds_read_b128 v[138:141], v186 offset:64
	v_add_f32_e32 v200, v200, v60
	v_add_f32_e32 v201, v201, v61
	v_cvt_pk_bf16_f32 v54, v60, v61
	v_exp_f32_e32 v72, v72
	v_exp_f32_e32 v73, v73
	s_mov_b32 s98, 0xd918000
	v_lshl_add_u64 v[146:147], v[120:121], 0, s[98:99]
	global_load_dwordx4 v[112:115], v[146:147], off offset:2304
	s_mov_b32 s98, 0xd940000
	s_waitcnt lgkmcnt(11)
	v_mfma_f32_32x32x16_bf16 v[16:31], v[142:145], v[48:51], v[16:31]
	ds_read_b128 v[142:145], v186 offset:4672
	v_add_f32_e32 v202, v202, v62
	v_add_f32_e32 v203, v203, v63
	v_cvt_pk_bf16_f32 v55, v62, v63
	v_exp_f32_e32 v74, v74
	v_exp_f32_e32 v75, v75
	v_lshl_add_u64 v[146:147], v[120:121], 0, s[98:99]
	global_load_dwordx4 v[116:119], v[146:147], off offset:2304
	s_mov_b32 s98, 0x17830000
	v_lshl_add_u64 v[146:147], v[124:125], 0, s[98:99]
	s_waitcnt lgkmcnt(11)
	v_mfma_f32_32x32x16_bf16 v[0:15], v[162:165], v[52:55], v[0:15]
	ds_read_b128 v[162:165], v186 offset:96
	v_exp_f32_e32 v76, v76
	v_exp_f32_e32 v77, v77
	global_load_dwordx4 v[120:123], v[146:147], off
	s_mov_b32 s98, 0x17838000
	v_lshl_add_u64 v[146:147], v[124:125], 0, s[98:99]
	global_load_dwordx4 v[124:127], v[146:147], off
	s_waitcnt lgkmcnt(11)
	v_mfma_f32_32x32x16_bf16 v[16:31], v[132:135], v[52:55], v[16:31]
	ds_read_b128 v[132:135], v186 offset:4704
	v_exp_f32_e32 v78, v78
	v_exp_f32_e32 v79, v79
	s_waitcnt lgkmcnt(11)
	v_mfma_f32_32x32x16_bf16 v[32:47], v[222:225], v[96:99], 0
	ds_read_b128 v[222:225], v186 offset:64512
	v_add_f32_e32 v188, v188, v64
	v_add_f32_e32 v189, v189, v65
	v_cvt_pk_bf16_f32 v64, v64, v65
	v_add_f32_e32 v190, v190, v66
	v_add_f32_e32 v191, v191, v67
	v_cvt_pk_bf16_f32 v65, v66, v67
	v_exp_f32_e32 v206, v206
	v_exp_f32_e32 v207, v207
	s_waitcnt lgkmcnt(11)
	v_mfma_f32_32x32x16_bf16 v[48:63], v[226:229], v[96:99], 0
	ds_read_b128 v[226:229], v187 offset:32256
	v_add_f32_e32 v192, v192, v68
	v_add_f32_e32 v193, v193, v69
	v_cvt_pk_bf16_f32 v66, v68, v69
	v_exp_f32_e32 v208, v208
	v_exp_f32_e32 v209, v209
	s_waitcnt lgkmcnt(11)
	v_mfma_f32_32x32x16_bf16 v[32:47], v[230:233], v[100:103], v[32:47]
	ds_read_b128 v[230:233], v186 offset:64544
	v_add_f32_e32 v194, v194, v70
	v_add_f32_e32 v195, v195, v71
	v_cvt_pk_bf16_f32 v67, v70, v71
	v_exp_f32_e32 v210, v210
	v_exp_f32_e32 v211, v211
	s_waitcnt lgkmcnt(9)
; __device__ __forceinline__ void attn_global(LAS unsigned char* lds, const bf16_t* __restrict__ PROJ, const bf16_t* __restrict__ VT, bf16_t* __restrict__ AO,
;                                             int rowbase, int S, int hq, int q0, float bound2) {
;     ...
;     int t = 0;
; #pragma unroll 1
;     for (; t + 10 < T; t += 4) { ATT_DSTEP(t, 0, true); ATT_DSTEP(t + 2, 2, true); }
; #pragma unroll 1
;     for (; t < T; t += 4) { ATT_DSTEP(t, 0, false); ATT_DSTEP(t + 2, 2, false); }
	v_mfma_f32_32x32x16_bf16 v[48:63], v[234:237], v[100:103], v[48:63]
	ds_read_b128 v[234:237], v187 offset:32288
	v_add_f32_e32 v196, v196, v72
	v_add_f32_e32 v197, v197, v73
	v_cvt_pk_bf16_f32 v68, v72, v73
	v_exp_f32_e32 v212, v212
	v_exp_f32_e32 v213, v213
	s_waitcnt lgkmcnt(7)
	v_mfma_f32_32x32x16_bf16 v[32:47], v[138:141], v[104:107], v[32:47]
	ds_read_b128 v[138:141], v186 offset:64576
	v_add_f32_e32 v198, v198, v74
	v_add_f32_e32 v199, v199, v75
	v_cvt_pk_bf16_f32 v69, v74, v75
	v_exp_f32_e32 v214, v214
	v_exp_f32_e32 v215, v215
	s_waitcnt lgkmcnt(7)
	v_mfma_f32_32x32x16_bf16 v[48:63], v[142:145], v[104:107], v[48:63]
	ds_read_b128 v[142:145], v187 offset:32320
	v_add_f32_e32 v200, v200, v76
	v_add_f32_e32 v201, v201, v77
	v_cvt_pk_bf16_f32 v70, v76, v77
	v_exp_f32_e32 v216, v216
	v_exp_f32_e32 v217, v217
	s_waitcnt lgkmcnt(7)
	v_mfma_f32_32x32x16_bf16 v[32:47], v[162:165], v[108:111], v[32:47]
	ds_read_b128 v[162:165], v186 offset:64608
	v_add_f32_e32 v202, v202, v78
	v_add_f32_e32 v203, v203, v79
	v_cvt_pk_bf16_f32 v71, v78, v79
	v_exp_f32_e32 v218, v218
	v_exp_f32_e32 v219, v219
	s_waitcnt lgkmcnt(7)
	v_mfma_f32_32x32x16_bf16 v[48:63], v[132:135], v[108:111], v[48:63]
	ds_read_b128 v[132:135], v187 offset:32352
	v_add_f32_e32 v188, v188, v206
	v_add_f32_e32 v189, v189, v207
	v_cvt_pk_bf16_f32 v206, v206, v207
	v_add_f32_e32 v190, v190, v208
	v_add_f32_e32 v191, v191, v209
	v_cvt_pk_bf16_f32 v207, v208, v209
	v_exp_f32_e32 v220, v220
	v_exp_f32_e32 v221, v221
	s_waitcnt lgkmcnt(7)
	v_mfma_f32_32x32x16_bf16 v[0:15], v[222:225], v[64:67], v[0:15]
	v_add_f32_e32 v192, v192, v210
	v_add_f32_e32 v193, v193, v211
	v_cvt_pk_bf16_f32 v208, v210, v211
	v_exp_f32_e32 v32, v32
	v_exp_f32_e32 v33, v33
	s_waitcnt lgkmcnt(6)
	v_mfma_f32_32x32x16_bf16 v[16:31], v[226:229], v[64:67], v[16:31]
	v_add_f32_e32 v194, v194, v212
	v_add_f32_e32 v195, v195, v213
	v_cvt_pk_bf16_f32 v209, v212, v213
	v_exp_f32_e32 v34, v34
	v_exp_f32_e32 v35, v35
	s_waitcnt lgkmcnt(5)
	v_mfma_f32_32x32x16_bf16 v[0:15], v[230:233], v[68:71], v[0:15]
	v_add_f32_e32 v196, v196, v214
	v_add_f32_e32 v197, v197, v215
	v_cvt_pk_bf16_f32 v210, v214, v215
	v_exp_f32_e32 v36, v36
	v_exp_f32_e32 v37, v37
	s_waitcnt lgkmcnt(4)
	v_mfma_f32_32x32x16_bf16 v[16:31], v[234:237], v[68:71], v[16:31]
	s_waitcnt lgkmcnt(0)
	s_barrier
	ds_read_b128 v[222:225], v186 offset:9216
	ds_read_b128 v[226:229], v186 offset:13824
	ds_read_b128 v[230:233], v186 offset:9248
	ds_read_b128 v[234:237], v186 offset:13856
	v_add_f32_e32 v198, v198, v216
	v_add_f32_e32 v199, v199, v217
	v_cvt_pk_bf16_f32 v211, v216, v217
	v_exp_f32_e32 v38, v38
	v_exp_f32_e32 v39, v39
	v_mfma_f32_32x32x16_bf16 v[0:15], v[138:141], v[206:209], v[0:15]
	ds_read_b128 v[138:141], v186 offset:9280
	v_add_f32_e32 v200, v200, v218
	v_add_f32_e32 v201, v201, v219
	v_cvt_pk_bf16_f32 v212, v218, v219
	v_exp_f32_e32 v40, v40
	v_exp_f32_e32 v41, v41
	v_mfma_f32_32x32x16_bf16 v[16:31], v[142:145], v[206:209], v[16:31]
	ds_read_b128 v[142:145], v186 offset:13888
	v_add_f32_e32 v202, v202, v220
	v_add_f32_e32 v203, v203, v221
	v_cvt_pk_bf16_f32 v213, v220, v221
	v_exp_f32_e32 v42, v42
	v_exp_f32_e32 v43, v43
	v_mfma_f32_32x32x16_bf16 v[0:15], v[162:165], v[210:213], v[0:15]
	ds_read_b128 v[162:165], v186 offset:9312
	v_exp_f32_e32 v44, v44
	v_exp_f32_e32 v45, v45
	v_mfma_f32_32x32x16_bf16 v[16:31], v[132:135], v[210:213], v[16:31]
	ds_read_b128 v[132:135], v186 offset:13920
	v_exp_f32_e32 v46, v46
	v_exp_f32_e32 v47, v47
	s_sub_u32 s98, s6, 6
	s_cmp_ge_u32 s98, s82
	s_cbranch_scc0 .Lattn_main
	s_waitcnt lgkmcnt(7)
	v_mfma_f32_32x32x16_bf16 v[64:79], v[222:225], v[96:99], 0
	ds_read_b128 v[222:225], v186 offset:36864
	v_add_f32_e32 v188, v188, v32
	v_add_f32_e32 v189, v189, v33
	v_cvt_pk_bf16_f32 v32, v32, v33
	v_add_f32_e32 v190, v190, v34
	v_add_f32_e32 v191, v191, v35
	v_cvt_pk_bf16_f32 v33, v34, v35
	v_exp_f32_e32 v48, v48
	v_exp_f32_e32 v49, v49
	s_waitcnt lgkmcnt(7)
	v_mfma_f32_32x32x16_bf16 v[206:221], v[226:229], v[96:99], 0
	ds_read_b128 v[226:229], v186 offset:41472
	v_add_f32_e32 v192, v192, v36
	v_add_f32_e32 v193, v193, v37
	v_cvt_pk_bf16_f32 v34, v36, v37
	v_exp_f32_e32 v50, v50
	v_exp_f32_e32 v51, v51
	s_waitcnt lgkmcnt(7)
	v_mfma_f32_32x32x16_bf16 v[64:79], v[230:233], v[100:103], v[64:79]
	ds_read_b128 v[230:233], v186 offset:36896
	v_add_f32_e32 v194, v194, v38
	v_add_f32_e32 v195, v195, v39
	v_cvt_pk_bf16_f32 v35, v38, v39
	v_exp_f32_e32 v52, v52
	v_exp_f32_e32 v53, v53
	s_waitcnt lgkmcnt(7)
	v_mfma_f32_32x32x16_bf16 v[206:221], v[234:237], v[100:103], v[206:221]
	ds_read_b128 v[234:237], v186 offset:41504
	v_add_f32_e32 v196, v196, v40
	v_add_f32_e32 v197, v197, v41
	v_cvt_pk_bf16_f32 v36, v40, v41
	v_exp_f32_e32 v54, v54
	v_exp_f32_e32 v55, v55
	s_waitcnt lgkmcnt(7)
	v_mfma_f32_32x32x16_bf16 v[64:79], v[138:141], v[104:107], v[64:79]
	ds_read_b128 v[138:141], v186 offset:36928
	v_add_f32_e32 v198, v198, v42
	v_add_f32_e32 v199, v199, v43
	v_cvt_pk_bf16_f32 v37, v42, v43
	v_exp_f32_e32 v56, v56
	v_exp_f32_e32 v57, v57
	s_waitcnt lgkmcnt(7)
	v_mfma_f32_32x32x16_bf16 v[206:221], v[142:145], v[104:107], v[206:221]
	ds_read_b128 v[142:145], v186 offset:41536
	v_add_f32_e32 v200, v200, v44
	v_add_f32_e32 v201, v201, v45
	v_cvt_pk_bf16_f32 v38, v44, v45
	v_exp_f32_e32 v58, v58
	v_exp_f32_e32 v59, v59
	s_waitcnt lgkmcnt(7)
	v_mfma_f32_32x32x16_bf16 v[64:79], v[162:165], v[108:111], v[64:79]
	ds_read_b128 v[162:165], v186 offset:36960
	v_add_f32_e32 v202, v202, v46
	v_add_f32_e32 v203, v203, v47
	v_cvt_pk_bf16_f32 v39, v46, v47
	v_exp_f32_e32 v60, v60
	v_exp_f32_e32 v61, v61
	s_waitcnt lgkmcnt(7)
; __device__ __forceinline__ void attn_global(LAS unsigned char* lds, const bf16_t* __restrict__ PROJ, const bf16_t* __restrict__ VT, bf16_t* __restrict__ AO,
;                                             int rowbase, int S, int hq, int q0, float bound2) {
;     ...
;     int t = 0;
; #pragma unroll 1
;     for (; t + 10 < T; t += 4) { ATT_DSTEP(t, 0, true); ATT_DSTEP(t + 2, 2, true); }
; #pragma unroll 1
;     for (; t < T; t += 4) { ATT_DSTEP(t, 0, false); ATT_DSTEP(t + 2, 2, false); }
	v_mfma_f32_32x32x16_bf16 v[206:221], v[132:135], v[108:111], v[206:221]
	ds_read_b128 v[132:135], v186 offset:41568
	v_add_f32_e32 v188, v188, v48
	v_add_f32_e32 v189, v189, v49
	v_cvt_pk_bf16_f32 v48, v48, v49
	v_add_f32_e32 v190, v190, v50
	v_add_f32_e32 v191, v191, v51
	v_cvt_pk_bf16_f32 v49, v50, v51
	v_exp_f32_e32 v62, v62
	v_exp_f32_e32 v63, v63
	s_waitcnt lgkmcnt(7)
	v_mfma_f32_32x32x16_bf16 v[0:15], v[222:225], v[32:35], v[0:15]
	ds_read_b128 v[222:225], v186 offset:18432
	v_add_f32_e32 v192, v192, v52
	v_add_f32_e32 v193, v193, v53
	v_cvt_pk_bf16_f32 v50, v52, v53
	v_exp_f32_e32 v64, v64
	v_exp_f32_e32 v65, v65
	s_waitcnt lgkmcnt(7)
	v_mfma_f32_32x32x16_bf16 v[16:31], v[226:229], v[32:35], v[16:31]
	ds_read_b128 v[226:229], v186 offset:23040
	v_add_f32_e32 v194, v194, v54
	v_add_f32_e32 v195, v195, v55
	v_cvt_pk_bf16_f32 v51, v54, v55
	v_exp_f32_e32 v66, v66
	v_exp_f32_e32 v67, v67
	s_waitcnt lgkmcnt(7)
	v_mfma_f32_32x32x16_bf16 v[0:15], v[230:233], v[36:39], v[0:15]
	ds_read_b128 v[230:233], v186 offset:18464
	v_add_f32_e32 v196, v196, v56
	v_add_f32_e32 v197, v197, v57
	v_cvt_pk_bf16_f32 v52, v56, v57
	v_exp_f32_e32 v68, v68
	v_exp_f32_e32 v69, v69
	v_add_u32_e32 v204, 0xd800, v136
	v_add_u32_e32 v205, 0xf800, v136
	s_waitcnt vmcnt(3)
	s_waitcnt lgkmcnt(7)
	v_mfma_f32_32x32x16_bf16 v[16:31], v[234:237], v[36:39], v[16:31]
	ds_read_b128 v[234:237], v186 offset:23072
	v_add_f32_e32 v198, v198, v58
	v_add_f32_e32 v199, v199, v59
	v_cvt_pk_bf16_f32 v53, v58, v59
	v_exp_f32_e32 v70, v70
	v_exp_f32_e32 v71, v71
	ds_write_b128 v168, v[112:115] offset:27648
	s_waitcnt vmcnt(2)
	ds_write_b128 v168, v[116:119]
	s_waitcnt lgkmcnt(9)
	v_mfma_f32_32x32x16_bf16 v[0:15], v[138:141], v[48:51], v[0:15]
	ds_read_b128 v[138:141], v186 offset:18496
	v_add_f32_e32 v200, v200, v60
	v_add_f32_e32 v201, v201, v61
	v_cvt_pk_bf16_f32 v54, v60, v61
	v_exp_f32_e32 v72, v72
	v_exp_f32_e32 v73, v73
	s_waitcnt vmcnt(1)
	ds_write2_b64 v204, v[120:121], v[122:123] offset1:2
	s_waitcnt vmcnt(0)
	s_waitcnt lgkmcnt(10)
	v_mfma_f32_32x32x16_bf16 v[16:31], v[142:145], v[48:51], v[16:31]
	ds_read_b128 v[142:145], v186 offset:23104
	v_add_f32_e32 v202, v202, v62
	v_add_f32_e32 v203, v203, v63
	v_cvt_pk_bf16_f32 v55, v62, v63
	v_exp_f32_e32 v74, v74
	v_exp_f32_e32 v75, v75
	ds_write2_b64 v205, v[124:125], v[126:127] offset0:128 offset1:130
	v_lshl_add_u64 v[120:121], v[128:129], 0, v[150:151]
	v_lshl_add_u64 v[124:125], v[130:131], 0, v[150:151]
	s_waitcnt lgkmcnt(11)
	v_mfma_f32_32x32x16_bf16 v[0:15], v[162:165], v[52:55], v[0:15]
	ds_read_b128 v[162:165], v186 offset:18528
	v_exp_f32_e32 v76, v76
	v_exp_f32_e32 v77, v77
	v_lshl_add_u64 v[128:129], v[128:129], 0, s[26:27]
	v_lshl_add_u64 v[130:131], v[130:131], 0, s[28:29]
	s_waitcnt lgkmcnt(11)
	v_mfma_f32_32x32x16_bf16 v[16:31], v[132:135], v[52:55], v[16:31]
	ds_read_b128 v[132:135], v186 offset:23136
	v_exp_f32_e32 v78, v78
	v_exp_f32_e32 v79, v79
	s_add_i32 s6, s6, 4
	s_waitcnt lgkmcnt(11)
	v_mfma_f32_32x32x16_bf16 v[32:47], v[222:225], v[96:99], 0
	ds_read_b128 v[222:225], v186 offset:46080
	v_add_f32_e32 v188, v188, v64
	v_add_f32_e32 v189, v189, v65
	v_cvt_pk_bf16_f32 v64, v64, v65
	v_add_f32_e32 v190, v190, v66
	v_add_f32_e32 v191, v191, v67
	v_cvt_pk_bf16_f32 v65, v66, v67
	v_exp_f32_e32 v206, v206
	v_exp_f32_e32 v207, v207
	s_waitcnt lgkmcnt(11)
	v_mfma_f32_32x32x16_bf16 v[48:63], v[226:229], v[96:99], 0
	ds_read_b128 v[226:229], v186 offset:50688
	v_add_f32_e32 v192, v192, v68
	v_add_f32_e32 v193, v193, v69
	v_cvt_pk_bf16_f32 v66, v68, v69
	v_exp_f32_e32 v208, v208
	v_exp_f32_e32 v209, v209
	s_waitcnt lgkmcnt(11)
	v_mfma_f32_32x32x16_bf16 v[32:47], v[230:233], v[100:103], v[32:47]
	ds_read_b128 v[230:233], v186 offset:46112
	v_add_f32_e32 v194, v194, v70
	v_add_f32_e32 v195, v195, v71
	v_cvt_pk_bf16_f32 v67, v70, v71
	v_exp_f32_e32 v210, v210
	v_exp_f32_e32 v211, v211
	s_waitcnt lgkmcnt(11)
	v_mfma_f32_32x32x16_bf16 v[48:63], v[234:237], v[100:103], v[48:63]
	ds_read_b128 v[234:237], v186 offset:50720
	v_add_f32_e32 v196, v196, v72
	v_add_f32_e32 v197, v197, v73
	v_cvt_pk_bf16_f32 v68, v72, v73
	v_exp_f32_e32 v212, v212
	v_exp_f32_e32 v213, v213
	s_waitcnt lgkmcnt(9)
	v_mfma_f32_32x32x16_bf16 v[32:47], v[138:141], v[104:107], v[32:47]
	ds_read_b128 v[138:141], v186 offset:46144
	v_add_f32_e32 v198, v198, v74
	v_add_f32_e32 v199, v199, v75
	v_cvt_pk_bf16_f32 v69, v74, v75
	v_exp_f32_e32 v214, v214
	v_exp_f32_e32 v215, v215
	s_waitcnt lgkmcnt(8)
	v_mfma_f32_32x32x16_bf16 v[48:63], v[142:145], v[104:107], v[48:63]
	ds_read_b128 v[142:145], v186 offset:50752
	v_add_f32_e32 v200, v200, v76
	v_add_f32_e32 v201, v201, v77
	v_cvt_pk_bf16_f32 v70, v76, v77
	v_exp_f32_e32 v216, v216
	v_exp_f32_e32 v217, v217
	s_waitcnt lgkmcnt(7)
	v_mfma_f32_32x32x16_bf16 v[32:47], v[162:165], v[108:111], v[32:47]
	ds_read_b128 v[162:165], v186 offset:46176
	v_add_f32_e32 v202, v202, v78
	v_add_f32_e32 v203, v203, v79
	v_cvt_pk_bf16_f32 v71, v78, v79
	v_exp_f32_e32 v218, v218
	v_exp_f32_e32 v219, v219
	s_waitcnt lgkmcnt(7)
	v_mfma_f32_32x32x16_bf16 v[48:63], v[132:135], v[108:111], v[48:63]
	ds_read_b128 v[132:135], v186 offset:50784
	v_add_f32_e32 v188, v188, v206
	v_add_f32_e32 v189, v189, v207
	v_cvt_pk_bf16_f32 v206, v206, v207
	v_add_f32_e32 v190, v190, v208
	v_add_f32_e32 v191, v191, v209
	v_cvt_pk_bf16_f32 v207, v208, v209
	v_exp_f32_e32 v220, v220
	v_exp_f32_e32 v221, v221
	s_waitcnt lgkmcnt(7)
	v_mfma_f32_32x32x16_bf16 v[0:15], v[222:225], v[64:67], v[0:15]
	v_add_f32_e32 v192, v192, v210
	v_add_f32_e32 v193, v193, v211
	v_cvt_pk_bf16_f32 v208, v210, v211
	v_exp_f32_e32 v32, v32
	v_exp_f32_e32 v33, v33
	s_waitcnt lgkmcnt(6)
	v_mfma_f32_32x32x16_bf16 v[16:31], v[226:229], v[64:67], v[16:31]
	v_add_f32_e32 v194, v194, v212
	v_add_f32_e32 v195, v195, v213
	v_cvt_pk_bf16_f32 v209, v212, v213
	v_exp_f32_e32 v34, v34
	v_exp_f32_e32 v35, v35
	s_waitcnt lgkmcnt(5)
	v_mfma_f32_32x32x16_bf16 v[0:15], v[230:233], v[68:71], v[0:15]
	v_add_f32_e32 v196, v196, v214
	v_add_f32_e32 v197, v197, v215
	v_cvt_pk_bf16_f32 v210, v214, v215
	v_exp_f32_e32 v36, v36
	v_exp_f32_e32 v37, v37
	s_waitcnt lgkmcnt(4)
	v_mfma_f32_32x32x16_bf16 v[16:31], v[234:237], v[68:71], v[16:31]
	s_waitcnt lgkmcnt(0)
	s_barrier
	ds_read_b128 v[222:225], v186 offset:27648
	ds_read_b128 v[226:229], v186 offset:32256
	ds_read_b128 v[230:233], v186 offset:27680
	ds_read_b128 v[234:237], v186 offset:32288
	v_add_f32_e32 v198, v198, v216
	v_add_f32_e32 v199, v199, v217
	v_cvt_pk_bf16_f32 v211, v216, v217
	v_exp_f32_e32 v38, v38
	v_exp_f32_e32 v39, v39
	v_mfma_f32_32x32x16_bf16 v[0:15], v[138:141], v[206:209], v[0:15]
	ds_read_b128 v[138:141], v186 offset:27712
	v_add_f32_e32 v200, v200, v218
	v_add_f32_e32 v201, v201, v219
	v_cvt_pk_bf16_f32 v212, v218, v219
	v_exp_f32_e32 v40, v40
	v_exp_f32_e32 v41, v41
	v_mfma_f32_32x32x16_bf16 v[16:31], v[142:145], v[206:209], v[16:31]
	ds_read_b128 v[142:145], v186 offset:32320
	v_add_f32_e32 v202, v202, v220
	v_add_f32_e32 v203, v203, v221
	v_cvt_pk_bf16_f32 v213, v220, v221
	v_exp_f32_e32 v42, v42
	v_exp_f32_e32 v43, v43
	v_mfma_f32_32x32x16_bf16 v[0:15], v[162:165], v[210:213], v[0:15]
	ds_read_b128 v[162:165], v186 offset:27744
	v_exp_f32_e32 v44, v44
	v_exp_f32_e32 v45, v45
	v_mfma_f32_32x32x16_bf16 v[16:31], v[132:135], v[210:213], v[16:31]
	ds_read_b128 v[132:135], v186 offset:32352
	v_exp_f32_e32 v46, v46
	v_exp_f32_e32 v47, v47
	s_waitcnt lgkmcnt(7)
	v_mfma_f32_32x32x16_bf16 v[64:79], v[222:225], v[96:99], 0
	ds_read_b128 v[222:225], v186 offset:55296
	v_add_f32_e32 v188, v188, v32
	v_add_f32_e32 v189, v189, v33
	v_cvt_pk_bf16_f32 v32, v32, v33
	v_add_f32_e32 v190, v190, v34
	v_add_f32_e32 v191, v191, v35
	v_cvt_pk_bf16_f32 v33, v34, v35
	v_exp_f32_e32 v48, v48
	v_exp_f32_e32 v49, v49
	s_waitcnt lgkmcnt(7)
	v_mfma_f32_32x32x16_bf16 v[206:221], v[226:229], v[96:99], 0
	ds_read_b128 v[226:229], v186 offset:59904
	v_add_f32_e32 v192, v192, v36
	v_add_f32_e32 v193, v193, v37
	v_cvt_pk_bf16_f32 v34, v36, v37
	v_exp_f32_e32 v50, v50
	v_exp_f32_e32 v51, v51
	s_waitcnt lgkmcnt(7)
	v_mfma_f32_32x32x16_bf16 v[64:79], v[230:233], v[100:103], v[64:79]
	ds_read_b128 v[230:233], v186 offset:55328
	v_add_f32_e32 v194, v194, v38
	v_add_f32_e32 v195, v195, v39
	v_cvt_pk_bf16_f32 v35, v38, v39
	v_exp_f32_e32 v52, v52
	v_exp_f32_e32 v53, v53
	s_waitcnt lgkmcnt(7)
	v_mfma_f32_32x32x16_bf16 v[206:221], v[234:237], v[100:103], v[206:221]
	ds_read_b128 v[234:237], v186 offset:59936
	v_add_f32_e32 v196, v196, v40
	v_add_f32_e32 v197, v197, v41
	v_cvt_pk_bf16_f32 v36, v40, v41
	v_exp_f32_e32 v54, v54
	v_exp_f32_e32 v55, v55
	s_waitcnt lgkmcnt(7)
	v_mfma_f32_32x32x16_bf16 v[64:79], v[138:141], v[104:107], v[64:79]
	ds_read_b128 v[138:141], v186 offset:55360
	v_add_f32_e32 v198, v198, v42
	v_add_f32_e32 v199, v199, v43
	v_cvt_pk_bf16_f32 v37, v42, v43
	v_exp_f32_e32 v56, v56
	v_exp_f32_e32 v57, v57
	s_waitcnt lgkmcnt(7)
	v_mfma_f32_32x32x16_bf16 v[206:221], v[142:145], v[104:107], v[206:221]
	ds_read_b128 v[142:145], v186 offset:59968
	v_add_f32_e32 v200, v200, v44
	v_add_f32_e32 v201, v201, v45
	v_cvt_pk_bf16_f32 v38, v44, v45
	v_exp_f32_e32 v58, v58
	v_exp_f32_e32 v59, v59
	s_waitcnt lgkmcnt(7)
	v_mfma_f32_32x32x16_bf16 v[64:79], v[162:165], v[108:111], v[64:79]
	ds_read_b128 v[162:165], v186 offset:55392
	v_add_f32_e32 v202, v202, v46
	v_add_f32_e32 v203, v203, v47
	v_cvt_pk_bf16_f32 v39, v46, v47
	v_exp_f32_e32 v60, v60
	v_exp_f32_e32 v61, v61
	s_waitcnt lgkmcnt(7)
	v_mfma_f32_32x32x16_bf16 v[206:221], v[132:135], v[108:111], v[206:221]
	ds_read_b128 v[132:135], v186 offset:60000
	v_add_f32_e32 v188, v188, v48
	v_add_f32_e32 v189, v189, v49
	v_cvt_pk_bf16_f32 v48, v48, v49
	v_add_f32_e32 v190, v190, v50
	v_add_f32_e32 v191, v191, v51
	v_cvt_pk_bf16_f32 v49, v50, v51
	v_exp_f32_e32 v62, v62
	v_exp_f32_e32 v63, v63
	s_waitcnt lgkmcnt(7)
	v_mfma_f32_32x32x16_bf16 v[0:15], v[222:225], v[32:35], v[0:15]
	v_add_f32_e32 v192, v192, v52
	v_add_f32_e32 v193, v193, v53
	v_cvt_pk_bf16_f32 v50, v52, v53
	v_exp_f32_e32 v64, v64
	v_exp_f32_e32 v65, v65
	s_waitcnt lgkmcnt(6)
	v_mfma_f32_32x32x16_bf16 v[16:31], v[226:229], v[32:35], v[16:31]
	v_add_f32_e32 v194, v194, v54
	v_add_f32_e32 v195, v195, v55
	v_cvt_pk_bf16_f32 v51, v54, v55
	v_exp_f32_e32 v66, v66
	v_exp_f32_e32 v67, v67
	s_waitcnt lgkmcnt(5)
; __device__ __forceinline__ void attn_global(LAS unsigned char* lds, const bf16_t* __restrict__ PROJ, const bf16_t* __restrict__ VT, bf16_t* __restrict__ AO,
;                                             int rowbase, int S, int hq, int q0, float bound2) {
;     ...
;     int t = 0;
; #pragma unroll 1
;     for (; t + 10 < T; t += 4) { ATT_DSTEP(t, 0, true); ATT_DSTEP(t + 2, 2, true); }
; #pragma unroll 1
;     for (; t < T; t += 4) { ATT_DSTEP(t, 0, false); ATT_DSTEP(t + 2, 2, false); }
	v_mfma_f32_32x32x16_bf16 v[0:15], v[230:233], v[36:39], v[0:15]
	v_add_f32_e32 v196, v196, v56
	v_add_f32_e32 v197, v197, v57
	v_cvt_pk_bf16_f32 v52, v56, v57
	v_exp_f32_e32 v68, v68
	v_exp_f32_e32 v69, v69
	s_waitcnt lgkmcnt(4)
	v_mfma_f32_32x32x16_bf16 v[16:31], v[234:237], v[36:39], v[16:31]
	v_add_f32_e32 v198, v198, v58
	v_add_f32_e32 v199, v199, v59
	v_cvt_pk_bf16_f32 v53, v58, v59
	v_exp_f32_e32 v70, v70
	v_exp_f32_e32 v71, v71
	s_waitcnt lgkmcnt(3)
	v_mfma_f32_32x32x16_bf16 v[0:15], v[138:141], v[48:51], v[0:15]
	v_add_f32_e32 v200, v200, v60
	v_add_f32_e32 v201, v201, v61
	v_cvt_pk_bf16_f32 v54, v60, v61
	v_exp_f32_e32 v72, v72
	v_exp_f32_e32 v73, v73
	s_waitcnt lgkmcnt(2)
	v_mfma_f32_32x32x16_bf16 v[16:31], v[142:145], v[48:51], v[16:31]
	v_add_f32_e32 v202, v202, v62
	v_add_f32_e32 v203, v203, v63
	v_cvt_pk_bf16_f32 v55, v62, v63
	v_exp_f32_e32 v74, v74
	v_exp_f32_e32 v75, v75
	s_waitcnt lgkmcnt(1)
	v_mfma_f32_32x32x16_bf16 v[0:15], v[162:165], v[52:55], v[0:15]
	v_exp_f32_e32 v76, v76
	v_exp_f32_e32 v77, v77
	s_waitcnt lgkmcnt(0)
	v_mfma_f32_32x32x16_bf16 v[16:31], v[132:135], v[52:55], v[16:31]
	v_exp_f32_e32 v78, v78
	v_exp_f32_e32 v79, v79
	ds_read_b128 v[222:225], v186 offset:64512
	v_add_f32_e32 v188, v188, v64
	v_add_f32_e32 v189, v189, v65
	v_cvt_pk_bf16_f32 v64, v64, v65
	v_add_f32_e32 v190, v190, v66
	v_add_f32_e32 v191, v191, v67
	v_cvt_pk_bf16_f32 v65, v66, v67
	v_exp_f32_e32 v206, v206
	v_exp_f32_e32 v207, v207
	ds_read_b128 v[226:229], v187 offset:32256
	v_add_f32_e32 v192, v192, v68
	v_add_f32_e32 v193, v193, v69
	v_cvt_pk_bf16_f32 v66, v68, v69
	v_exp_f32_e32 v208, v208
	v_exp_f32_e32 v209, v209
	ds_read_b128 v[230:233], v186 offset:64544
	v_add_f32_e32 v194, v194, v70
	v_add_f32_e32 v195, v195, v71
	v_cvt_pk_bf16_f32 v67, v70, v71
	v_exp_f32_e32 v210, v210
	v_exp_f32_e32 v211, v211
	ds_read_b128 v[234:237], v187 offset:32288
	v_add_f32_e32 v196, v196, v72
	v_add_f32_e32 v197, v197, v73
	v_cvt_pk_bf16_f32 v68, v72, v73
	v_exp_f32_e32 v212, v212
	v_exp_f32_e32 v213, v213
	ds_read_b128 v[138:141], v186 offset:64576
	v_add_f32_e32 v198, v198, v74
	v_add_f32_e32 v199, v199, v75
	v_cvt_pk_bf16_f32 v69, v74, v75
	v_exp_f32_e32 v214, v214
	v_exp_f32_e32 v215, v215
	ds_read_b128 v[142:145], v187 offset:32320
	v_add_f32_e32 v200, v200, v76
	v_add_f32_e32 v201, v201, v77
	v_cvt_pk_bf16_f32 v70, v76, v77
	v_exp_f32_e32 v216, v216
	v_exp_f32_e32 v217, v217
	ds_read_b128 v[162:165], v186 offset:64608
	v_add_f32_e32 v202, v202, v78
	v_add_f32_e32 v203, v203, v79
	v_cvt_pk_bf16_f32 v71, v78, v79
	v_exp_f32_e32 v218, v218
	v_exp_f32_e32 v219, v219
	ds_read_b128 v[132:135], v187 offset:32352
	v_add_f32_e32 v188, v188, v206
	v_add_f32_e32 v189, v189, v207
	v_cvt_pk_bf16_f32 v206, v206, v207
	v_add_f32_e32 v190, v190, v208
	v_add_f32_e32 v191, v191, v209
	v_cvt_pk_bf16_f32 v207, v208, v209
	v_exp_f32_e32 v220, v220
	v_exp_f32_e32 v221, v221
	s_waitcnt lgkmcnt(7)
	v_mfma_f32_32x32x16_bf16 v[0:15], v[222:225], v[64:67], v[0:15]
	v_add_f32_e32 v192, v192, v210
	v_add_f32_e32 v193, v193, v211
	v_cvt_pk_bf16_f32 v208, v210, v211
	s_nop 0
	s_nop 0
	s_waitcnt lgkmcnt(6)
	v_mfma_f32_32x32x16_bf16 v[16:31], v[226:229], v[64:67], v[16:31]
	v_add_f32_e32 v194, v194, v212
	v_add_f32_e32 v195, v195, v213
	v_cvt_pk_bf16_f32 v209, v212, v213
	s_nop 0
	s_nop 0
	s_waitcnt lgkmcnt(5)
	v_mfma_f32_32x32x16_bf16 v[0:15], v[230:233], v[68:71], v[0:15]
	v_add_f32_e32 v196, v196, v214
	v_add_f32_e32 v197, v197, v215
	v_cvt_pk_bf16_f32 v210, v214, v215
	s_nop 0
	s_nop 0
	s_waitcnt lgkmcnt(4)
	v_mfma_f32_32x32x16_bf16 v[16:31], v[234:237], v[68:71], v[16:31]
	s_waitcnt lgkmcnt(0)
	s_barrier
	v_add_f32_e32 v198, v198, v216
	v_add_f32_e32 v199, v199, v217
	v_cvt_pk_bf16_f32 v211, v216, v217
	s_nop 0
	s_nop 0
	v_mfma_f32_32x32x16_bf16 v[0:15], v[138:141], v[206:209], v[0:15]
	v_add_f32_e32 v200, v200, v218
	v_add_f32_e32 v201, v201, v219
	v_cvt_pk_bf16_f32 v212, v218, v219
	s_nop 0
	s_nop 0
	v_mfma_f32_32x32x16_bf16 v[16:31], v[142:145], v[206:209], v[16:31]
	v_add_f32_e32 v202, v202, v220
	v_add_f32_e32 v203, v203, v221
	v_cvt_pk_bf16_f32 v213, v220, v221
	s_nop 0
	s_nop 0
	v_mfma_f32_32x32x16_bf16 v[0:15], v[162:165], v[210:213], v[0:15]
	v_mfma_f32_32x32x16_bf16 v[16:31], v[132:135], v[210:213], v[16:31]
